# prep: W_in conversion job index decomposed k-chunk-fastest (full-line writes), x row loads nt
# speedup vs baseline: 1.0152x; 1.0043x over previous
.LBB0_809:
	s_and_b32 s27, s20, 63
	s_lshr_b32 s19, s20, 6
	s_lshl_b32 s26, s19, 6
	s_cmp_gt_i32 s19, 63
	s_mov_b64 s[16:17], -1
	s_cbranch_scc0 .LBB0_811
	s_add_i32 s18, s26, 0xfffff000
	s_mov_b64 s[16:17], 0
.LBB0_811:
	s_andn2_b64 vcc, exec, s[16:17]
	s_cbranch_vccnz .LBB0_813
	s_and_b32 s16, s26, 64
	s_bitcmp0_b32 s19, 1
	s_cselect_b32 s17, s59, 0x1000
	s_lshl_b32 s18, s19, 5
	s_and_b32 s18, s18, 0xffffff80
	s_add_i32 s17, s17, s18
	s_or_b32 s18, s17, s16

.LBB0_826:
	s_or_b64 exec, exec, s[6:7]
	v_cmp_ne_u64_e64 s[6:7], 0, v[0:1]
	v_lshl_add_u64 v[36:37], v[0:1], 0, v[192:193]
	v_mov_b32_e32 v0, 0
	v_mov_b32_e32 v4, 0
	v_mov_b32_e32 v5, 0
	v_mov_b32_e32 v6, 0
	v_mov_b32_e32 v7, 0
	s_and_saveexec_b64 s[22:23], s[6:7]
	s_cbranch_execz .LBB0_828
	global_load_dwordx4 v[4:7], v[36:37], off nt
.LBB0_828:
	s_or_b64 exec, exec, s[22:23]
	v_mov_b32_e32 v1, 0
	v_mov_b32_e32 v2, 0
	v_mov_b32_e32 v3, 0
	s_and_saveexec_b64 s[22:23], s[6:7]
	s_cbranch_execz .LBB0_830
	global_load_dwordx4 v[0:3], v[36:37], off offset:1024 nt
.LBB0_830:
	s_or_b64 exec, exec, s[22:23]
	v_mov_b32_e32 v8, 0
	v_mov_b32_e32 v12, 0
	v_mov_b32_e32 v13, 0
	v_mov_b32_e32 v14, 0
	v_mov_b32_e32 v15, 0
	s_and_saveexec_b64 s[22:23], s[6:7]
	s_cbranch_execz .LBB0_832
	global_load_dwordx4 v[12:15], v[36:37], off offset:2048 nt
.LBB0_832:
	s_or_b64 exec, exec, s[22:23]
	v_mov_b32_e32 v9, 0
	v_mov_b32_e32 v10, 0
	v_mov_b32_e32 v11, 0
	s_and_saveexec_b64 s[22:23], s[6:7]
	s_cbranch_execz .LBB0_834
	global_load_dwordx4 v[8:11], v[36:37], off offset:3072 nt
.LBB0_834:
	s_or_b64 exec, exec, s[22:23]
	v_mov_b32_e32 v16, 0
	v_mov_b32_e32 v20, 0
	v_mov_b32_e32 v21, 0
	v_mov_b32_e32 v22, 0
	v_mov_b32_e32 v23, 0
	s_and_saveexec_b64 s[22:23], s[6:7]
	s_cbranch_execz .LBB0_836
	v_add_co_u32_e32 v18, vcc, 0x1000, v36
	s_nop 1
	v_addc_co_u32_e32 v19, vcc, 0, v37, vcc
	global_load_dwordx4 v[20:23], v[18:19], off nt
.LBB0_836:
	s_or_b64 exec, exec, s[22:23]
	v_mov_b32_e32 v17, 0
	v_mov_b32_e32 v18, 0
	v_mov_b32_e32 v19, 0
	s_and_saveexec_b64 s[22:23], s[6:7]
	s_cbranch_execz .LBB0_838
	v_add_co_u32_e32 v16, vcc, 0x1000, v36
	s_nop 1
	v_addc_co_u32_e32 v17, vcc, 0, v37, vcc
	global_load_dwordx4 v[16:19], v[16:17], off offset:1024 nt
.LBB0_838:
	s_or_b64 exec, exec, s[22:23]
	v_mov_b32_e32 v24, 0
	v_mov_b32_e32 v28, 0
	v_mov_b32_e32 v29, 0
	v_mov_b32_e32 v30, 0
	v_mov_b32_e32 v31, 0
	s_and_saveexec_b64 s[22:23], s[6:7]
	s_cbranch_execz .LBB0_840
	v_add_co_u32_e32 v26, vcc, 0x1000, v36
	s_nop 1
	v_addc_co_u32_e32 v27, vcc, 0, v37, vcc
	global_load_dwordx4 v[28:31], v[26:27], off offset:2048 nt
.LBB0_840:
	s_or_b64 exec, exec, s[22:23]
	v_mov_b32_e32 v25, 0
	v_mov_b32_e32 v26, 0
	v_mov_b32_e32 v27, 0
	s_and_saveexec_b64 s[22:23], s[6:7]
	s_cbranch_execz .LBB0_817
	v_add_co_u32_e32 v24, vcc, 0x1000, v36
	s_nop 1
	v_addc_co_u32_e32 v25, vcc, 0, v37, vcc
	global_load_dwordx4 v[24:27], v[24:25], off offset:3072 nt
	s_branch .LBB0_817
